# global grid barriers too: every workgroup invalidates L1 on arrival, the XCD leader invalidates (L1 + non-local L2 lines) after its write-back under the top-level exchange, nobody invalidates after th
# speedup vs baseline: 1.0853x; 1.0222x over previous
.Lnl_dec:
	s_mov_b32 s100, 1
	s_cmp_eq_u32 s100, 1
	s_cbranch_scc0 .Lnl_noinv
	buffer_inv sc1

.Lbar_global:
	s_mov_b64 s[4:5], exec
	buffer_wbl2 sc1
	s_waitcnt lgkmcnt(0)
	s_waitcnt vmcnt(0)
	buffer_inv sc1
	v_mbcnt_lo_u32_b32 v3, s4, 0
	v_mbcnt_hi_u32_b32 v3, s5, v3
	v_cmp_eq_u32_e32 vcc, 0, v3
	s_and_saveexec_b64 s[6:7], vcc
	s_cbranch_execz .LBB0_44
	s_bcnt1_i32_b64 s4, s[4:5]
	v_mov_b32_e32 v4, s4
	v_readlane_b32 s4, v253, 10
	v_readlane_b32 s5, v253, 11
	s_nop 4
	global_atomic_add v4, v131, v4, s[4:5] sc0

.LBB0_58:
	s_or_b64 exec, exec, s[4:5]
	s_mov_b64 s[4:5], exec
	v_mbcnt_lo_u32_b32 v2, s4, 0
	v_mbcnt_hi_u32_b32 v2, s5, v2
	v_cmp_eq_u32_e32 vcc, 0, v2
	s_waitcnt vmcnt(0)
	s_and_saveexec_b64 s[6:7], vcc
	s_cbranch_execz .LBB0_60
	s_bcnt1_i32_b64 s4, s[4:5]
	v_mov_b32_e32 v2, s4
	v_readlane_b32 s4, v253, 8
	v_readlane_b32 s5, v253, 9
	s_nop 4
	global_atomic_add v131, v2, s[4:5]
.LBB0_60:
	s_or_b64 exec, exec, s[6:7]
	s_waitcnt vmcnt(0)
